# cache policy: chunk records stored nt; loads of freshly written data (attention outputs, yraw in merge; ybf in final norm) no longer nt
# speedup vs baseline: 1.0047x; 1.0047x over previous
.LBB0_1221:
	s_or_b64 exec, exec, s[10:11]
	s_cmpk_lt_i32 s2, 0x800
	s_cselect_b64 s[10:11], -1, 0
	s_and_b64 vcc, exec, s[10:11]
	s_waitcnt lgkmcnt(0)
	s_barrier
	s_cbranch_vccz .LBB0_1224
	v_readlane_b32 s46, v246, 38
	v_readlane_b32 s47, v246, 39
	v_readlane_b32 s48, v246, 40
	v_readlane_b32 s49, v246, 41
	v_lshrrev_b32_e32 v0, 6, v141
	v_and_b32_e32 v1, 63, v141
	s_mov_b32 s44, 0xbfb8aa3b
	v_readfirstlane_b32 s13, v0
	s_mov_b32 s45, 0xbfb8aa3b
	v_lshlrev_b32_e32 v4, 4, v1
	v_lshrrev_b32_e32 v2, 3, v1
	v_lshlrev_b32_e32 v0, 5, v1
	v_lshlrev_b32_e32 v5, 2, v2
	v_mul_u32_u24_e32 v6, 0x318000, v2
	global_load_dwordx4 v[8:11], v0, s[46:47]
	global_load_dwordx4 v[12:15], v0, s[46:47] offset:16
	global_load_dwordx4 v[16:19], v0, s[48:49]
	global_load_dwordx4 v[20:23], v0, s[48:49] offset:16
	v_and_b32_e32 v7, 7, v1
	v_lshrrev_b32_e32 v2, 1, v7
	v_and_b32_e32 v7, 1, v7
	v_lshlrev_b32_e32 v2, 9, v2
	v_lshlrev_b32_e32 v7, 6, v7
	v_add3_u32 v7, v6, v2, v7
	v_mov_b32_e32 v100, 0x3a27c5ac
	v_and_b32_e32 v101, 15, v1
	v_lshlrev_b32_e32 v101, 2, v101
	s_add_i32 s16, s2, 0
	s_and_b32 s17, s16, 7
	s_lshr_b32 s12, s16, 3
	s_add_i32 s22, s90, 0
	s_lshr_b32 s22, s22, 3
	s_lshl_b32 s91, s17, 12
	s_add_i32 s91, s91, s13
	s_lshl_b32 s17, s17, 6
	s_add_i32 s17, s17, 0x4000
	s_add_u32 s74, s88, s17
	s_addc_u32 s75, s89, 0
	s_movk_i32 s56, 0x8000
	s_lshl_b32 s16, s12, 4
	s_add_i32 s16, s16, s91
	s_mul_i32 s17, s16, 0x2100
	s_add_u32 s24, s78, s17
	s_addc_u32 s25, s79, 0
	s_add_u32 s26, s24, 0x1900
	s_addc_u32 s27, s25, 0
	s_lshl_b32 s17, s16, 10
	s_add_u32 s28, s80, s17
	s_addc_u32 s29, s81, 0
	s_lshr_b32 s17, s16, 12
	s_lshl_b32 s17, s17, 11
	s_bfe_u32 s19, s16, 0x80004
	s_add_i32 s17, s17, s19
	s_mul_i32 s17, s17, 0x3180
	s_add_u32 s68, s86, s17
	s_addc_u32 s69, s87, 0
	s_and_b32 s19, s16, 15
	s_lshl_b32 s17, s19, 2
	s_addk_i32 s17, 0x3100
	s_add_u32 s30, s68, s17
	s_addc_u32 s31, s69, 0
	s_lshr_b32 s17, s19, 2
	s_lshl_b32 s17, s17, 7
	s_and_b32 s19, s19, 3
	s_lshl_b32 s19, s19, 1
	s_add_i32 s17, s17, s19
	s_addk_i32 s17, 0x2800
	s_add_u32 s70, s68, s17
	s_addc_u32 s71, s69, 0
	global_load_dword v24, v5, s[24:25] offset:3072
	global_load_dword v25, v5, s[24:25] offset:3104
	global_load_dword v26, v5, s[24:25] offset:3136
	global_load_dwordx4 v[28:31], v4, s[24:25]
	global_load_dwordx4 v[32:35], v4, s[24:25] offset:1024
	global_load_dwordx4 v[36:39], v4, s[24:25] offset:2048
	global_load_dwordx4 v[44:47], v4, s[26:27] offset:1024 nt
	global_load_dwordx4 v[48:51], v4, s[28:29]
	global_load_dwordx4 v[52:55], v4, s[26:27] nt
	global_load_dword v27, v6, s[30:31]
	global_load_ushort v56, v7, s[70:71] offset:0
	global_load_ushort v57, v7, s[70:71] offset:8
	global_load_ushort v58, v7, s[70:71] offset:16
	global_load_ushort v59, v7, s[70:71] offset:24
	global_load_ushort v60, v7, s[70:71] offset:32
	global_load_ushort v61, v7, s[70:71] offset:40
	global_load_ushort v62, v7, s[70:71] offset:48
	global_load_ushort v63, v7, s[70:71] offset:56
	s_mov_b32 s50, 1
.Lfm_loop:
	s_lshl_b32 s16, s12, 4
	s_add_i32 s16, s16, s91
	s_add_i32 s16, s16, 8
	s_mul_i32 s17, s16, 0x2100
	s_add_u32 s58, s78, s17
	s_addc_u32 s59, s79, 0
	s_add_u32 s60, s58, 0x1900
	s_addc_u32 s61, s59, 0
	s_lshl_b32 s17, s16, 10
	s_add_u32 s62, s80, s17
	s_addc_u32 s63, s81, 0
	s_lshr_b32 s17, s16, 12
	s_lshl_b32 s17, s17, 11
	s_bfe_u32 s19, s16, 0x80004
	s_add_i32 s17, s17, s19
	s_mul_i32 s17, s17, 0x3180
	s_add_u32 s68, s86, s17
	s_addc_u32 s69, s87, 0
	s_and_b32 s19, s16, 15
	s_lshl_b32 s17, s19, 2
	s_addk_i32 s17, 0x3100
	s_add_u32 s64, s68, s17
	s_addc_u32 s65, s69, 0
	s_lshr_b32 s17, s19, 2
	s_lshl_b32 s17, s17, 7
	s_and_b32 s19, s19, 3
	s_lshl_b32 s19, s19, 1
	s_add_i32 s17, s17, s19
	s_addk_i32 s17, 0x2800
	s_add_u32 s66, s68, s17
	s_addc_u32 s67, s69, 0
	global_load_dword v64, v5, s[58:59] offset:3072
	global_load_dword v65, v5, s[58:59] offset:3104
	global_load_dword v66, v5, s[58:59] offset:3136
	global_load_dwordx4 v[68:71], v4, s[58:59]
	global_load_dwordx4 v[72:75], v4, s[58:59] offset:1024
	global_load_dwordx4 v[76:79], v4, s[58:59] offset:2048
	global_load_dwordx4 v[80:83], v4, s[60:61] offset:1024 nt
	global_load_dwordx4 v[84:87], v4, s[62:63]
	global_load_dwordx4 v[88:91], v4, s[60:61] nt
	global_load_dword v67, v6, s[64:65]
	global_load_ushort v92, v7, s[66:67] offset:0
	global_load_ushort v93, v7, s[66:67] offset:8
	global_load_ushort v94, v7, s[66:67] offset:16
	global_load_ushort v95, v7, s[66:67] offset:24
	global_load_ushort v96, v7, s[66:67] offset:32
	global_load_ushort v97, v7, s[66:67] offset:40
	global_load_ushort v98, v7, s[66:67] offset:48
	global_load_ushort v99, v7, s[66:67] offset:56
	s_cmp_eq_u32 s50, 0
	s_cbranch_scc1 .Lfm_w20
	s_waitcnt vmcnt(18)
	s_branch .Lfm_wdone

.Lfm_wdone:
	v_max3_f32 v127, v24, v25, v26
	v_sub_f32_e32 v102, v24, v127
	v_sub_f32_e32 v104, v25, v127
	v_sub_f32_e32 v106, v26, v127
	v_mul_f32_e32 v102, 0x3fb8aa3b, v102
	v_mul_f32_e32 v104, 0x3fb8aa3b, v104
	v_mul_f32_e32 v106, 0x3fb8aa3b, v106
	v_exp_f32_e32 v102, v102
	v_exp_f32_e32 v104, v104
	v_exp_f32_e32 v106, v106
	s_nop 0
	v_add_f32_e32 v127, v102, v104
	v_add_f32_e32 v127, v106, v127
	v_div_scale_f32 v122, s[72:73], v127, v127, 1.0
	v_rcp_f32_e32 v123, v122
	v_div_scale_f32 v124, vcc, 1.0, v127, 1.0
	v_fma_f32 v126, -v122, v123, 1.0
	v_fmac_f32_e32 v123, v126, v123
	v_mul_f32_e32 v125, v124, v123
	v_fma_f32 v126, -v122, v125, v124
	v_fmac_f32_e32 v125, v126, v123
	v_fma_f32 v122, -v122, v125, v124
	v_div_fmas_f32 v122, v122, v123, v125
	v_div_fixup_f32 v103, v122, v127, 1.0
	v_mul_f32_e32 v102, v102, v103
	v_mul_f32_e32 v104, v104, v103
	v_mul_f32_e32 v106, v106, v103
	v_lshlrev_b32_e32 v108, 16, v28
	v_and_b32_e32 v109, 0xffff0000, v28
	v_lshlrev_b32_e32 v110, 16, v32
	v_and_b32_e32 v111, 0xffff0000, v32
	v_lshlrev_b32_e32 v112, 16, v36
	v_and_b32_e32 v113, 0xffff0000, v36
	v_lshlrev_b32_e32 v114, 16, v44
	v_and_b32_e32 v115, 0xffff0000, v44
	v_pk_mul_f32 v[116:117], v[108:109], v[102:103] op_sel_hi:[1,0]
	v_pk_fma_f32 v[116:117], v[110:111], v[104:105], v[116:117] op_sel_hi:[1,0,1]
	v_pk_fma_f32 v[116:117], v[112:113], v[106:107], v[116:117] op_sel_hi:[1,0,1]
	v_pk_mul_f32 v[118:119], v[114:115], s[44:45]
	v_exp_f32_e32 v118, v118
	v_exp_f32_e32 v119, v119
	s_nop 0
	v_pk_add_f32 v[118:119], v[118:119], 1.0 op_sel_hi:[1,0]
	v_div_scale_f32 v122, s[72:73], v118, v118, v114
	v_rcp_f32_e32 v123, v122
	v_div_scale_f32 v124, vcc, v114, v118, v114
	v_fma_f32 v126, -v122, v123, 1.0
	v_fmac_f32_e32 v123, v126, v123
	v_mul_f32_e32 v125, v124, v123
	v_fma_f32 v126, -v122, v125, v124
	v_fmac_f32_e32 v125, v126, v123
	v_fma_f32 v122, -v122, v125, v124
	v_div_fmas_f32 v122, v122, v123, v125
	v_div_fixup_f32 v120, v122, v118, v114
	v_div_scale_f32 v122, s[72:73], v119, v119, v115
	v_rcp_f32_e32 v123, v122
	v_div_scale_f32 v124, vcc, v115, v119, v115
	v_fma_f32 v126, -v122, v123, 1.0
	v_fmac_f32_e32 v123, v126, v123
	v_mul_f32_e32 v125, v124, v123
	v_fma_f32 v126, -v122, v125, v124
	v_fmac_f32_e32 v125, v126, v123
	v_fma_f32 v122, -v122, v125, v124
	v_div_fmas_f32 v122, v122, v123, v125
	v_div_fixup_f32 v121, v122, v119, v115
	v_pk_mul_f32 v[116:117], v[120:121], v[116:117]
	v_cvt_pk_bf16_f32 v128, v116, v117
	v_lshlrev_b32_e32 v108, 16, v29
	v_and_b32_e32 v109, 0xffff0000, v29
	v_lshlrev_b32_e32 v110, 16, v33
	v_and_b32_e32 v111, 0xffff0000, v33
	v_lshlrev_b32_e32 v112, 16, v37
	v_and_b32_e32 v113, 0xffff0000, v37
	v_lshlrev_b32_e32 v114, 16, v45
	v_and_b32_e32 v115, 0xffff0000, v45
	v_pk_mul_f32 v[116:117], v[108:109], v[102:103] op_sel_hi:[1,0]
	v_pk_fma_f32 v[116:117], v[110:111], v[104:105], v[116:117] op_sel_hi:[1,0,1]
	v_pk_fma_f32 v[116:117], v[112:113], v[106:107], v[116:117] op_sel_hi:[1,0,1]
	v_pk_mul_f32 v[118:119], v[114:115], s[44:45]
	v_exp_f32_e32 v118, v118
	v_exp_f32_e32 v119, v119
	s_nop 0
	v_pk_add_f32 v[118:119], v[118:119], 1.0 op_sel_hi:[1,0]
	v_div_scale_f32 v122, s[72:73], v118, v118, v114
	v_rcp_f32_e32 v123, v122
	v_div_scale_f32 v124, vcc, v114, v118, v114
	v_fma_f32 v126, -v122, v123, 1.0
	v_fmac_f32_e32 v123, v126, v123
	v_mul_f32_e32 v125, v124, v123
	v_fma_f32 v126, -v122, v125, v124
	v_fmac_f32_e32 v125, v126, v123
	v_fma_f32 v122, -v122, v125, v124
	v_div_fmas_f32 v122, v122, v123, v125
	v_div_fixup_f32 v120, v122, v118, v114
	v_div_scale_f32 v122, s[72:73], v119, v119, v115
	v_rcp_f32_e32 v123, v122
	v_div_scale_f32 v124, vcc, v115, v119, v115
	v_fma_f32 v126, -v122, v123, 1.0
	v_fmac_f32_e32 v123, v126, v123
	v_mul_f32_e32 v125, v124, v123
	v_fma_f32 v126, -v122, v125, v124
	v_fmac_f32_e32 v125, v126, v123
	v_fma_f32 v122, -v122, v125, v124
	v_div_fmas_f32 v122, v122, v123, v125
	v_div_fixup_f32 v121, v122, v119, v115
	v_pk_mul_f32 v[116:117], v[120:121], v[116:117]
	v_cvt_pk_bf16_f32 v129, v116, v117
	v_lshlrev_b32_e32 v108, 16, v30
	v_and_b32_e32 v109, 0xffff0000, v30
	v_lshlrev_b32_e32 v110, 16, v34
	v_and_b32_e32 v111, 0xffff0000, v34
	v_lshlrev_b32_e32 v112, 16, v38
	v_and_b32_e32 v113, 0xffff0000, v38
	v_lshlrev_b32_e32 v114, 16, v46
	v_and_b32_e32 v115, 0xffff0000, v46
	v_pk_mul_f32 v[116:117], v[108:109], v[102:103] op_sel_hi:[1,0]
	v_pk_fma_f32 v[116:117], v[110:111], v[104:105], v[116:117] op_sel_hi:[1,0,1]
	v_pk_fma_f32 v[116:117], v[112:113], v[106:107], v[116:117] op_sel_hi:[1,0,1]
	v_pk_mul_f32 v[118:119], v[114:115], s[44:45]
	v_exp_f32_e32 v118, v118
	v_exp_f32_e32 v119, v119
	s_nop 0
	v_pk_add_f32 v[118:119], v[118:119], 1.0 op_sel_hi:[1,0]
	v_div_scale_f32 v122, s[72:73], v118, v118, v114
	v_rcp_f32_e32 v123, v122
	v_div_scale_f32 v124, vcc, v114, v118, v114
	v_fma_f32 v126, -v122, v123, 1.0
	v_fmac_f32_e32 v123, v126, v123
	v_mul_f32_e32 v125, v124, v123
	v_fma_f32 v126, -v122, v125, v124
	v_fmac_f32_e32 v125, v126, v123
	v_fma_f32 v122, -v122, v125, v124
	v_div_fmas_f32 v122, v122, v123, v125
	v_div_fixup_f32 v120, v122, v118, v114
	v_div_scale_f32 v122, s[72:73], v119, v119, v115
	v_rcp_f32_e32 v123, v122
	v_div_scale_f32 v124, vcc, v115, v119, v115
	v_fma_f32 v126, -v122, v123, 1.0
	v_fmac_f32_e32 v123, v126, v123
	v_mul_f32_e32 v125, v124, v123
	v_fma_f32 v126, -v122, v125, v124
	v_fmac_f32_e32 v125, v126, v123
	v_fma_f32 v122, -v122, v125, v124
	v_div_fmas_f32 v122, v122, v123, v125
	v_div_fixup_f32 v121, v122, v119, v115
	v_pk_mul_f32 v[116:117], v[120:121], v[116:117]
	v_cvt_pk_bf16_f32 v130, v116, v117
	v_lshlrev_b32_e32 v108, 16, v31
	v_and_b32_e32 v109, 0xffff0000, v31
	v_lshlrev_b32_e32 v110, 16, v35
	v_and_b32_e32 v111, 0xffff0000, v35
	v_lshlrev_b32_e32 v112, 16, v39
	v_and_b32_e32 v113, 0xffff0000, v39
	v_lshlrev_b32_e32 v114, 16, v47
	v_and_b32_e32 v115, 0xffff0000, v47
	v_pk_mul_f32 v[116:117], v[108:109], v[102:103] op_sel_hi:[1,0]
	v_pk_fma_f32 v[116:117], v[110:111], v[104:105], v[116:117] op_sel_hi:[1,0,1]
	v_pk_fma_f32 v[116:117], v[112:113], v[106:107], v[116:117] op_sel_hi:[1,0,1]
	v_pk_mul_f32 v[118:119], v[114:115], s[44:45]
	v_exp_f32_e32 v118, v118
	v_exp_f32_e32 v119, v119
	s_nop 0
	v_pk_add_f32 v[118:119], v[118:119], 1.0 op_sel_hi:[1,0]
	v_div_scale_f32 v122, s[72:73], v118, v118, v114
	v_rcp_f32_e32 v123, v122
	v_div_scale_f32 v124, vcc, v114, v118, v114
	v_fma_f32 v126, -v122, v123, 1.0
	v_fmac_f32_e32 v123, v126, v123
	v_mul_f32_e32 v125, v124, v123
	v_fma_f32 v126, -v122, v125, v124
	v_fmac_f32_e32 v125, v126, v123
	v_fma_f32 v122, -v122, v125, v124
	v_div_fmas_f32 v122, v122, v123, v125
	v_div_fixup_f32 v120, v122, v118, v114
	v_div_scale_f32 v122, s[72:73], v119, v119, v115
	v_rcp_f32_e32 v123, v122
	v_div_scale_f32 v124, vcc, v115, v119, v115
	v_fma_f32 v126, -v122, v123, 1.0
	v_fmac_f32_e32 v123, v126, v123
	v_mul_f32_e32 v125, v124, v123
	v_fma_f32 v126, -v122, v125, v124
	v_fmac_f32_e32 v125, v126, v123
	v_fma_f32 v122, -v122, v125, v124
	v_div_fmas_f32 v122, v122, v123, v125
	v_div_fixup_f32 v121, v122, v119, v115
	v_pk_mul_f32 v[116:117], v[120:121], v[116:117]
	v_cvt_pk_bf16_f32 v131, v116, v117
	global_store_dwordx4 v4, v[128:131], s[26:27] offset:1024
	v_lshlrev_b32_e32 v28, 16, v48
	v_and_b32_e32 v29, 0xffff0000, v48
	v_lshlrev_b32_e32 v30, 16, v49
	v_and_b32_e32 v31, 0xffff0000, v49
	v_lshlrev_b32_e32 v32, 16, v50
	v_and_b32_e32 v33, 0xffff0000, v50
	v_lshlrev_b32_e32 v34, 16, v51
	v_and_b32_e32 v35, 0xffff0000, v51
	v_lshlrev_b32_e32 v36, 16, v52
	v_and_b32_e32 v37, 0xffff0000, v52
	v_lshlrev_b32_e32 v38, 16, v53
	v_and_b32_e32 v39, 0xffff0000, v53
	v_lshlrev_b32_e32 v44, 16, v54
	v_and_b32_e32 v45, 0xffff0000, v54
	v_lshlrev_b32_e32 v46, 16, v55
	v_and_b32_e32 v47, 0xffff0000, v55
	v_lshlrev_b32_e32 v56, 16, v56
	v_lshlrev_b32_e32 v57, 16, v57
	v_lshlrev_b32_e32 v58, 16, v58
	v_lshlrev_b32_e32 v59, 16, v59
	v_lshlrev_b32_e32 v60, 16, v60
	v_lshlrev_b32_e32 v61, 16, v61
	v_lshlrev_b32_e32 v62, 16, v62
	v_lshlrev_b32_e32 v63, 16, v63
	v_add_f32_e32 v108, v28, v29
	v_add_f32_e32 v108, v108, v30
	v_add_f32_e32 v108, v108, v31
	v_add_f32_e32 v108, v108, v32
	v_add_f32_e32 v108, v108, v33
	v_add_f32_e32 v108, v108, v34
	v_add_f32_e32 v108, v108, v35
	s_nop 1
	v_add_f32_dpp v109, v108, v108 quad_perm:[1,0,3,2] row_mask:0xf bank_mask:0xf
	s_nop 1
	v_add_f32_dpp v108, v109, v109 quad_perm:[2,3,0,1] row_mask:0xf bank_mask:0xf
	s_nop 1
	v_add_f32_dpp v109, v108, v108 row_half_mirror row_mask:0xf bank_mask:0xf
	v_mov_b32_e32 v108, v109
	v_mul_f32_e32 v108, 0x3c800000, v108
	v_pk_add_f32 v[28:29], v[28:29], v[108:109] op_sel_hi:[1,0] neg_lo:[0,1] neg_hi:[0,1]
	v_pk_add_f32 v[30:31], v[30:31], v[108:109] op_sel_hi:[1,0] neg_lo:[0,1] neg_hi:[0,1]
	v_pk_add_f32 v[32:33], v[32:33], v[108:109] op_sel_hi:[1,0] neg_lo:[0,1] neg_hi:[0,1]
	v_pk_add_f32 v[34:35], v[34:35], v[108:109] op_sel_hi:[1,0] neg_lo:[0,1] neg_hi:[0,1]
	v_pk_mul_f32 v[110:111], v[28:29], v[28:29]
	v_pk_mul_f32 v[112:113], v[30:31], v[30:31]
	v_pk_mul_f32 v[114:115], v[32:33], v[32:33]
	v_pk_mul_f32 v[116:117], v[34:35], v[34:35]
	v_add_f32_e32 v118, v110, v111
	v_add_f32_e32 v118, v112, v118
	v_add_f32_e32 v118, v113, v118
	v_add_f32_e32 v118, v114, v118
	v_add_f32_e32 v118, v115, v118
	v_add_f32_e32 v118, v116, v118
	v_add_f32_e32 v118, v117, v118
	s_nop 1
	v_add_f32_dpp v119, v118, v118 quad_perm:[1,0,3,2] row_mask:0xf bank_mask:0xf
	s_nop 1
	v_add_f32_dpp v118, v119, v119 quad_perm:[2,3,0,1] row_mask:0xf bank_mask:0xf
	s_nop 1
	v_add_f32_dpp v119, v118, v118 row_half_mirror row_mask:0xf bank_mask:0xf
	v_mov_b32_e32 v118, v119
	v_fmamk_f32 v118, v118, 0x3c800000, v100
	v_rsq_f32_e32 v118, v118
	v_mov_b32_e32 v120, v27
	v_pk_mul_f32 v[28:29], v[28:29], v[118:119] op_sel_hi:[1,0]
	v_pk_mul_f32 v[30:31], v[30:31], v[118:119] op_sel_hi:[1,0]
	v_pk_mul_f32 v[32:33], v[32:33], v[118:119] op_sel_hi:[1,0]
	v_pk_mul_f32 v[34:35], v[34:35], v[118:119] op_sel_hi:[1,0]
	v_pk_fma_f32 v[28:29], v[8:9], v[28:29], v[16:17]
	v_pk_fma_f32 v[30:31], v[10:11], v[30:31], v[18:19]
	v_pk_fma_f32 v[32:33], v[12:13], v[32:33], v[20:21]
	v_pk_fma_f32 v[34:35], v[14:15], v[34:35], v[22:23]
	v_pk_fma_f32 v[28:29], v[120:121], v[56:57], v[28:29] op_sel_hi:[0,1,1]
	v_pk_fma_f32 v[30:31], v[120:121], v[58:59], v[30:31] op_sel_hi:[0,1,1]
	v_pk_fma_f32 v[32:33], v[120:121], v[60:61], v[32:33] op_sel_hi:[0,1,1]
	v_pk_fma_f32 v[34:35], v[120:121], v[62:63], v[34:35] op_sel_hi:[0,1,1]
	v_pk_mul_f32 v[118:119], v[36:37], s[44:45]
	v_exp_f32_e32 v118, v118
	v_exp_f32_e32 v119, v119
	s_nop 0
	v_pk_add_f32 v[118:119], v[118:119], 1.0 op_sel_hi:[1,0]
	v_div_scale_f32 v122, s[72:73], v118, v118, v36
	v_rcp_f32_e32 v123, v122
	v_div_scale_f32 v124, vcc, v36, v118, v36
	v_fma_f32 v126, -v122, v123, 1.0
	v_fmac_f32_e32 v123, v126, v123
	v_mul_f32_e32 v125, v124, v123
	v_fma_f32 v126, -v122, v125, v124
	v_fmac_f32_e32 v125, v126, v123
	v_fma_f32 v122, -v122, v125, v124
	v_div_fmas_f32 v122, v122, v123, v125
	v_div_fixup_f32 v108, v122, v118, v36
	v_div_scale_f32 v122, s[72:73], v119, v119, v37
	v_rcp_f32_e32 v123, v122
	v_div_scale_f32 v124, vcc, v37, v119, v37
	v_fma_f32 v126, -v122, v123, 1.0
	v_fmac_f32_e32 v123, v126, v123
	v_mul_f32_e32 v125, v124, v123
	v_fma_f32 v126, -v122, v125, v124
	v_fmac_f32_e32 v125, v126, v123
	v_fma_f32 v122, -v122, v125, v124
	v_div_fmas_f32 v122, v122, v123, v125
	v_div_fixup_f32 v109, v122, v119, v37
	v_pk_mul_f32 v[28:29], v[108:109], v[28:29]
	v_cvt_pk_bf16_f32 v132, v28, v29
	v_pk_mul_f32 v[118:119], v[38:39], s[44:45]
	v_exp_f32_e32 v118, v118
	v_exp_f32_e32 v119, v119
	s_nop 0
	v_pk_add_f32 v[118:119], v[118:119], 1.0 op_sel_hi:[1,0]
	v_div_scale_f32 v122, s[72:73], v118, v118, v38
	v_rcp_f32_e32 v123, v122
	v_div_scale_f32 v124, vcc, v38, v118, v38
	v_fma_f32 v126, -v122, v123, 1.0
	v_fmac_f32_e32 v123, v126, v123
	v_mul_f32_e32 v125, v124, v123
	v_fma_f32 v126, -v122, v125, v124
	v_fmac_f32_e32 v125, v126, v123
	v_fma_f32 v122, -v122, v125, v124
	v_div_fmas_f32 v122, v122, v123, v125
	v_div_fixup_f32 v108, v122, v118, v38
	v_div_scale_f32 v122, s[72:73], v119, v119, v39
	v_rcp_f32_e32 v123, v122
	v_div_scale_f32 v124, vcc, v39, v119, v39
	v_fma_f32 v126, -v122, v123, 1.0
	v_fmac_f32_e32 v123, v126, v123
	v_mul_f32_e32 v125, v124, v123
	v_fma_f32 v126, -v122, v125, v124
	v_fmac_f32_e32 v125, v126, v123
	v_fma_f32 v122, -v122, v125, v124
	v_div_fmas_f32 v122, v122, v123, v125
	v_div_fixup_f32 v109, v122, v119, v39
	v_pk_mul_f32 v[30:31], v[108:109], v[30:31]
	v_cvt_pk_bf16_f32 v133, v30, v31
	v_pk_mul_f32 v[118:119], v[44:45], s[44:45]
	v_exp_f32_e32 v118, v118
	v_exp_f32_e32 v119, v119
	s_nop 0
	v_pk_add_f32 v[118:119], v[118:119], 1.0 op_sel_hi:[1,0]
	v_div_scale_f32 v122, s[72:73], v118, v118, v44
	v_rcp_f32_e32 v123, v122
	v_div_scale_f32 v124, vcc, v44, v118, v44
	v_fma_f32 v126, -v122, v123, 1.0
	v_fmac_f32_e32 v123, v126, v123
	v_mul_f32_e32 v125, v124, v123
	v_fma_f32 v126, -v122, v125, v124
	v_fmac_f32_e32 v125, v126, v123
	v_fma_f32 v122, -v122, v125, v124
	v_div_fmas_f32 v122, v122, v123, v125
	v_div_fixup_f32 v108, v122, v118, v44
	v_div_scale_f32 v122, s[72:73], v119, v119, v45
	v_rcp_f32_e32 v123, v122
	v_div_scale_f32 v124, vcc, v45, v119, v45
	v_fma_f32 v126, -v122, v123, 1.0
	v_fmac_f32_e32 v123, v126, v123
	v_mul_f32_e32 v125, v124, v123
	v_fma_f32 v126, -v122, v125, v124
	v_fmac_f32_e32 v125, v126, v123
	v_fma_f32 v122, -v122, v125, v124
	v_div_fmas_f32 v122, v122, v123, v125
	v_div_fixup_f32 v109, v122, v119, v45
	v_pk_mul_f32 v[32:33], v[108:109], v[32:33]
	v_cvt_pk_bf16_f32 v134, v32, v33
	v_pk_mul_f32 v[118:119], v[46:47], s[44:45]
	v_exp_f32_e32 v118, v118
	v_exp_f32_e32 v119, v119
	s_nop 0
	v_pk_add_f32 v[118:119], v[118:119], 1.0 op_sel_hi:[1,0]
	v_div_scale_f32 v122, s[72:73], v118, v118, v46
	v_rcp_f32_e32 v123, v122
	v_div_scale_f32 v124, vcc, v46, v118, v46
	v_fma_f32 v126, -v122, v123, 1.0
	v_fmac_f32_e32 v123, v126, v123
	v_mul_f32_e32 v125, v124, v123
	v_fma_f32 v126, -v122, v125, v124
	v_fmac_f32_e32 v125, v126, v123
	v_fma_f32 v122, -v122, v125, v124
	v_div_fmas_f32 v122, v122, v123, v125
	v_div_fixup_f32 v108, v122, v118, v46
	v_div_scale_f32 v122, s[72:73], v119, v119, v47
	v_rcp_f32_e32 v123, v122
	v_div_scale_f32 v124, vcc, v47, v119, v47
	v_fma_f32 v126, -v122, v123, 1.0
	v_fmac_f32_e32 v123, v126, v123
	v_mul_f32_e32 v125, v124, v123
	v_fma_f32 v126, -v122, v125, v124
	v_fmac_f32_e32 v125, v126, v123
	v_fma_f32 v122, -v122, v125, v124
	v_div_fmas_f32 v122, v122, v123, v125
	v_div_fixup_f32 v109, v122, v119, v47
	v_pk_mul_f32 v[34:35], v[108:109], v[34:35]
	v_cvt_pk_bf16_f32 v135, v34, v35
	global_store_dwordx4 v4, v[132:135], s[26:27]
	s_mov_b32 s50, 0
	s_add_i32 s12, s12, s22
	s_cmpk_lt_i32 s12, 0x100
	s_cbranch_scc0 .Lfm_nonext
	s_lshl_b32 s16, s12, 4
	s_add_i32 s16, s16, s91
	s_mul_i32 s17, s16, 0x2100
	s_add_u32 s24, s78, s17
	s_addc_u32 s25, s79, 0
	s_add_u32 s26, s24, 0x1900
	s_addc_u32 s27, s25, 0
	s_lshl_b32 s17, s16, 10
	s_add_u32 s28, s80, s17
	s_addc_u32 s29, s81, 0
	s_lshr_b32 s17, s16, 12
	s_lshl_b32 s17, s17, 11
	s_bfe_u32 s19, s16, 0x80004
	s_add_i32 s17, s17, s19
	s_mul_i32 s17, s17, 0x3180
	s_add_u32 s68, s86, s17
	s_addc_u32 s69, s87, 0
	s_and_b32 s19, s16, 15
	s_lshl_b32 s17, s19, 2
	s_addk_i32 s17, 0x3100
	s_add_u32 s30, s68, s17
	s_addc_u32 s31, s69, 0
	s_lshr_b32 s17, s19, 2
	s_lshl_b32 s17, s17, 7
	s_and_b32 s19, s19, 3
	s_lshl_b32 s19, s19, 1
	s_add_i32 s17, s17, s19
	s_addk_i32 s17, 0x2800
	s_add_u32 s70, s68, s17
	s_addc_u32 s71, s69, 0
	global_load_dword v24, v5, s[24:25] offset:3072
	global_load_dword v25, v5, s[24:25] offset:3104
	global_load_dword v26, v5, s[24:25] offset:3136
	global_load_dwordx4 v[28:31], v4, s[24:25]
	global_load_dwordx4 v[32:35], v4, s[24:25] offset:1024
	global_load_dwordx4 v[36:39], v4, s[24:25] offset:2048
	global_load_dwordx4 v[44:47], v4, s[26:27] offset:1024 nt
	global_load_dwordx4 v[48:51], v4, s[28:29]
	global_load_dwordx4 v[52:55], v4, s[26:27] nt
	global_load_dword v27, v6, s[30:31]
	global_load_ushort v56, v7, s[70:71] offset:0
	global_load_ushort v57, v7, s[70:71] offset:8
	global_load_ushort v58, v7, s[70:71] offset:16
	global_load_ushort v59, v7, s[70:71] offset:24
	global_load_ushort v60, v7, s[70:71] offset:32
	global_load_ushort v61, v7, s[70:71] offset:40
	global_load_ushort v62, v7, s[70:71] offset:48
	global_load_ushort v63, v7, s[70:71] offset:56
	s_waitcnt vmcnt(20)
	s_branch .Lfm_cb

.LBB0_1356:
	v_ashrrev_i32_e32 v7, 31, v6
	v_lshlrev_b64 v[10:11], 11, v[6:7]
	v_lshl_add_u64 v[14:15], v[2:3], 0, v[10:11]
	global_load_dwordx4 v[10:13], v[14:15], off offset:1024
	global_load_dwordx4 v[16:19], v[14:15], off offset:3072
	global_load_dwordx4 v[20:23], v[14:15], off
	global_load_dwordx4 v[24:27], v[14:15], off offset:2048
	global_load_dwordx4 v[28:31], v[0:1], off
	global_load_dwordx4 v[32:35], v[0:1], off offset:16
	s_add_i32 s2, s2, s90
	s_cmpk_gt_i32 s2, 0x7ff
	s_waitcnt vmcnt(5)
	v_lshlrev_b32_e32 v37, 16, v11
	v_lshlrev_b32_e32 v36, 16, v10
	v_and_b32_e32 v39, 0xffff0000, v11
	v_and_b32_e32 v38, 0xffff0000, v10
	v_lshlrev_b32_e32 v41, 16, v13
	v_lshlrev_b32_e32 v40, 16, v12
	v_and_b32_e32 v43, 0xffff0000, v13
	v_and_b32_e32 v42, 0xffff0000, v12
	s_waitcnt vmcnt(4)
	v_lshlrev_b32_e32 v13, 16, v17
	v_lshlrev_b32_e32 v12, 16, v16
	v_and_b32_e32 v11, 0xffff0000, v17
	v_and_b32_e32 v10, 0xffff0000, v16
	v_lshlrev_b32_e32 v17, 16, v19
	v_lshlrev_b32_e32 v16, 16, v18
	v_and_b32_e32 v15, 0xffff0000, v19
	v_and_b32_e32 v14, 0xffff0000, v18
	s_waitcnt vmcnt(3)
	v_lshlrev_b32_e32 v18, 16, v22
	v_and_b32_e32 v19, 0xffff0000, v22
	v_lshlrev_b32_e32 v22, 16, v23
	v_and_b32_e32 v23, 0xffff0000, v23
	v_lshlrev_b32_e32 v44, 16, v20
	v_and_b32_e32 v45, 0xffff0000, v20
	v_lshlrev_b32_e32 v46, 16, v21
	v_and_b32_e32 v47, 0xffff0000, v21
	s_waitcnt vmcnt(2)
	v_lshlrev_b32_e32 v48, 16, v26
	v_and_b32_e32 v49, 0xffff0000, v26
	v_lshlrev_b32_e32 v26, 16, v27
	v_and_b32_e32 v27, 0xffff0000, v27
	v_lshlrev_b32_e32 v50, 16, v24
	v_and_b32_e32 v51, 0xffff0000, v24
	v_lshlrev_b32_e32 v52, 16, v25
	v_and_b32_e32 v53, 0xffff0000, v25
	v_mov_b32_e32 v60, v23
	v_mov_b32_e32 v61, v19
	v_pk_mul_f32 v[62:63], v[44:45], v[44:45]
	v_pk_mul_f32 v[64:65], v[46:47], v[46:47]
	v_mov_b32_e32 v58, v22
	v_mov_b32_e32 v59, v18
	v_mov_b32_e32 v68, v27
	v_mov_b32_e32 v69, v49
	v_pk_mul_f32 v[70:71], v[50:51], v[50:51]
	v_pk_mul_f32 v[72:73], v[52:53], v[52:53]
	v_pk_mul_f32 v[60:61], v[60:61], v[60:61]
	v_add_f32_e32 v9, v64, v65
	v_add_f32_e32 v64, v62, v63
	v_mov_b32_e32 v66, v26
	v_mov_b32_e32 v67, v48
	v_pk_mul_f32 v[62:63], v[68:69], v[68:69]
	v_add_f32_e32 v65, v72, v73
	v_add_f32_e32 v68, v70, v71
	v_pk_fma_f32 v[58:59], v[58:59], v[58:59], v[60:61]
	v_add_f32_e32 v9, v64, v9
	v_pk_mul_f32 v[20:21], v[38:39], v[38:39]
	v_pk_fma_f32 v[60:61], v[66:67], v[66:67], v[62:63]
	v_add_f32_e32 v62, v68, v65
	v_add_f32_e32 v9, v59, v9
	v_pk_mul_f32 v[54:55], v[10:11], v[10:11]
	v_pk_fma_f32 v[20:21], v[36:37], v[36:37], v[20:21]
	v_add_f32_e32 v59, v61, v62
	v_add_f32_e32 v9, v58, v9
	v_pk_mul_f32 v[24:25], v[42:43], v[42:43]
	v_pk_fma_f32 v[54:55], v[12:13], v[12:13], v[54:55]
	v_add_f32_e32 v58, v60, v59
	v_add_f32_e32 v9, v20, v9
	v_pk_mul_f32 v[56:57], v[14:15], v[14:15]
	v_pk_fma_f32 v[24:25], v[40:41], v[40:41], v[24:25]
	v_add_f32_e32 v20, v54, v58
	v_add_f32_e32 v9, v21, v9
	v_pk_fma_f32 v[56:57], v[16:17], v[16:17], v[56:57]
	v_add_f32_e32 v20, v55, v20
	v_add_f32_e32 v9, v24, v9
	v_add_f32_e32 v20, v56, v20
	v_add_f32_e32 v9, v25, v9
	v_add_f32_e32 v20, v57, v20
	v_mov_b32_e32 v21, v9
	v_mov_b32_e32 v24, v20
	s_nop 0
	v_mov_b32_dpp v21, v21 quad_perm:[1,0,3,2] row_mask:0xf bank_mask:0xf
	v_mov_b32_dpp v24, v24 quad_perm:[1,0,3,2] row_mask:0xf bank_mask:0xf
	v_add_f32_e32 v9, v9, v21
	v_add_f32_e32 v20, v20, v24
	v_mov_b32_e32 v21, v9
	v_mov_b32_e32 v24, v20
	s_nop 0
	v_mov_b32_dpp v21, v21 quad_perm:[2,3,0,1] row_mask:0xf bank_mask:0xf
	v_mov_b32_dpp v24, v24 quad_perm:[2,3,0,1] row_mask:0xf bank_mask:0xf
	v_add_f32_e32 v9, v9, v21
	v_add_f32_e32 v24, v20, v24
	v_mov_b32_e32 v20, v9
	s_nop 1
	v_mov_b32_dpp v20, v20 row_half_mirror row_mask:0xf bank_mask:0xf
	v_add_f32_e32 v9, v9, v20
	v_mov_b32_e32 v20, v9
	s_nop 1
	v_mov_b32_dpp v20, v20 row_mirror row_mask:0xf bank_mask:0xf
	v_add_f32_e32 v9, v9, v20
	s_nop 0
	v_readlane_b32 s4, v9, 0
	v_readlane_b32 s6, v9, 16
	v_readlane_b32 s5, v9, 32
	v_readlane_b32 s7, v9, 48
	v_mov_b32_e32 v9, v24
	v_mov_b32_e32 v20, s6
	v_mov_b32_e32 v21, s7
	v_mov_b32_dpp v9, v9 row_half_mirror row_mask:0xf bank_mask:0xf
	v_add_f32_e32 v9, v24, v9
	v_mov_b32_e32 v24, v9
	v_pk_add_f32 v[20:21], s[4:5], v[20:21]
	s_nop 0
	v_mov_b32_dpp v24, v24 row_mirror row_mask:0xf bank_mask:0xf
	v_add_f32_e32 v9, v9, v24
	v_mov_b32_e32 v55, v20
	v_readlane_b32 s6, v9, 16
	v_readlane_b32 s7, v9, 48
	v_readlane_b32 s4, v9, 0
	v_readlane_b32 s5, v9, 32
	v_mov_b32_e32 v24, s6
	v_mov_b32_e32 v25, s7
	v_pk_add_f32 v[24:25], s[4:5], v[24:25]
	s_nop 0
	v_mov_b32_e32 v54, v24
	v_mov_b32_e32 v20, v25
	v_pk_add_f32 v[20:21], v[54:55], v[20:21]
	s_nop 0
	v_pk_fma_f32 v[54:55], v[20:21], s[0:1], v[8:9] op_sel_hi:[1,0,0]
	v_lshlrev_b64 v[20:21], 12, v[6:7]
	v_mul_f32_e32 v9, 0x4b800000, v55
	v_cmp_gt_f32_e32 vcc, s3, v55
	v_lshl_add_u64 v[56:57], v[4:5], 0, v[20:21]
	s_nop 0
	v_cndmask_b32_e32 v9, v55, v9, vcc
	v_rsq_f32_e32 v9, v9
	s_nop 0
	v_mul_f32_e32 v7, 0x45800000, v9
	v_cndmask_b32_e32 v58, v9, v7, vcc
	v_pk_mul_f32 v[20:21], v[58:59], v[22:23] op_sel_hi:[0,1]
	v_pk_mul_f32 v[22:23], v[58:59], v[44:45] op_sel_hi:[0,1]
	v_pk_mul_f32 v[24:25], v[58:59], v[46:47] op_sel_hi:[0,1]
	v_pk_mul_f32 v[18:19], v[58:59], v[18:19] op_sel_hi:[0,1]
	s_waitcnt vmcnt(1)
	v_pk_mul_f32 v[24:25], v[30:31], v[24:25]
	v_pk_mul_f32 v[22:23], v[28:29], v[22:23]
	s_waitcnt vmcnt(0)
	v_pk_mul_f32 v[18:19], v[32:33], v[18:19]
	v_pk_mul_f32 v[20:21], v[34:35], v[20:21]
	global_store_dwordx4 v[56:57], v[22:25], off nt
	global_store_dwordx4 v[56:57], v[18:21], off offset:16 nt
	global_load_dwordx4 v[18:21], v[0:1], off offset:2048
	s_nop 0
	global_load_dwordx4 v[22:25], v[0:1], off offset:2064
	v_mov_b32_e32 v28, v36
	v_mov_b32_e32 v29, v38
	v_mov_b32_e32 v38, v37
	v_mov_b32_e32 v30, v40
	v_mov_b32_e32 v31, v42
	v_mov_b32_e32 v42, v41
	v_pk_mul_f32 v[28:29], v[58:59], v[28:29] op_sel_hi:[0,1]
	v_pk_mul_f32 v[32:33], v[58:59], v[38:39] op_sel_hi:[0,1]
	v_pk_mul_f32 v[30:31], v[58:59], v[30:31] op_sel_hi:[0,1]
	v_pk_mul_f32 v[34:35], v[58:59], v[42:43] op_sel_hi:[0,1]
	v_mul_f32_e32 v7, 0x4b800000, v54
	v_cmp_gt_f32_e32 vcc, s3, v54
	s_waitcnt vmcnt(1)
	v_pk_mul_f32 v[18:19], v[28:29], v[18:19]
	v_pk_mul_f32 v[20:21], v[32:33], v[20:21]
	s_waitcnt vmcnt(0)
	v_pk_mul_f32 v[22:23], v[30:31], v[22:23]
	v_pk_mul_f32 v[24:25], v[34:35], v[24:25]
	global_store_dwordx4 v[56:57], v[18:21], off offset:2048 nt
	global_store_dwordx4 v[56:57], v[22:25], off offset:2064 nt
	global_load_dwordx4 v[18:21], v[0:1], off offset:16
	s_nop 0
	global_load_dwordx4 v[22:25], v[0:1], off
	v_cndmask_b32_e32 v7, v54, v7, vcc
	v_rsq_f32_e32 v7, v7
	v_add_u32_e32 v28, 1, v6
	v_ashrrev_i32_e32 v29, 31, v28
	v_lshlrev_b64 v[28:29], 12, v[28:29]
	v_mul_f32_e32 v9, 0x45800000, v7
	v_cndmask_b32_e32 v30, v7, v9, vcc
	v_pk_mul_f32 v[34:35], v[30:31], v[52:53] op_sel_hi:[0,1]
	v_pk_mul_f32 v[36:37], v[30:31], v[50:51] op_sel_hi:[0,1]
	v_lshl_add_u64 v[28:29], v[4:5], 0, v[28:29]
	v_pk_mul_f32 v[32:33], v[30:31], v[48:49] op_sel_hi:[0,1]
	v_pk_mul_f32 v[26:27], v[30:31], v[26:27] op_sel_hi:[0,1]
	v_add_u32_e32 v6, s1, v6
	s_waitcnt vmcnt(1)
	v_pk_mul_f32 v[18:19], v[18:19], v[32:33]
	s_waitcnt vmcnt(0)
	v_pk_mul_f32 v[22:23], v[22:23], v[36:37]
	v_pk_mul_f32 v[24:25], v[24:25], v[34:35]
	v_pk_mul_f32 v[20:21], v[20:21], v[26:27]
	global_store_dwordx4 v[28:29], v[22:25], off nt
	global_store_dwordx4 v[28:29], v[18:21], off offset:16 nt
	global_load_dwordx4 v[18:21], v[0:1], off offset:2048
	s_nop 0
	global_load_dwordx4 v[22:25], v[0:1], off offset:2064
	v_mov_b32_e32 v26, v12
	v_mov_b32_e32 v27, v10
	v_mov_b32_e32 v10, v13
	v_mov_b32_e32 v32, v16
	v_mov_b32_e32 v33, v14
	v_mov_b32_e32 v14, v17
	v_pk_mul_f32 v[12:13], v[30:31], v[26:27] op_sel_hi:[0,1]
	v_pk_mul_f32 v[26:27], v[30:31], v[10:11] op_sel_hi:[0,1]
	v_pk_mul_f32 v[16:17], v[30:31], v[32:33] op_sel_hi:[0,1]
	v_pk_mul_f32 v[30:31], v[30:31], v[14:15] op_sel_hi:[0,1]
	s_waitcnt vmcnt(1)
	v_pk_mul_f32 v[10:11], v[12:13], v[18:19]
	v_pk_mul_f32 v[12:13], v[26:27], v[20:21]
	s_waitcnt vmcnt(0)
	v_pk_mul_f32 v[14:15], v[16:17], v[22:23]
	v_pk_mul_f32 v[16:17], v[30:31], v[24:25]
	global_store_dwordx4 v[28:29], v[10:13], off offset:2048 nt
	global_store_dwordx4 v[28:29], v[14:17], off offset:2064 nt
	s_cbranch_scc0 .LBB0_1356
